# phase 0b cache conversion: six pieces per thread loaded together, converted and stored directly (four load-wait-store loops skipped)
# speedup vs baseline: 1.0050x; 1.0017x over previous
.LBB0_89:
	s_or_b64 exec, exec, s[0:1]
	v_mov_b32_e32 v10, v187
	v_readlane_b32 s0, v247, 0
	s_barrier
	s_mov_b32 s1, 0x20000
	v_lshl_add_u32 v0, s0, 8, v10
	s_lshl_b32 s0, s84, 8
	v_cmp_gt_i32_e32 vcc, s1, v0
	v_ashrrev_i32_e32 v1, 31, v0
	s_and_saveexec_b64 s[2:3], vcc
	s_cbranch_execz .LBB0_94
	v_lshlrev_b64 v[2:3], 4, v[0:1]
	v_readlane_b32 s52, v247, 5
	v_readlane_b32 s53, v247, 6
	v_readlane_b32 s54, v247, 7
	v_readlane_b32 s55, v247, 8
	v_readlane_b32 s56, v247, 9
	v_readlane_b32 s57, v247, 10
	v_readlane_b32 s58, v247, 11
	v_readlane_b32 s59, v247, 12
	v_lshlrev_b32_e32 v100, 4, v0
	s_lshl_b32 s60, s84, 12
	v_add_u32_e32 v101, s60, v100
	v_lshlrev_b32_e32 v102, 3, v0
	s_lshl_b32 s61, s84, 11
	v_add_u32_e32 v103, s61, v102
	s_nop 2
	global_load_dwordx4 v[104:107], v100, s[52:53]
	global_load_dwordx4 v[108:111], v100, s[54:55]
	global_load_dwordx4 v[112:115], v100, s[56:57]
	global_load_dwordx4 v[116:119], v101, s[56:57]
	global_load_dwordx4 v[120:123], v100, s[58:59]
	global_load_dwordx4 v[124:127], v101, s[58:59]
	s_waitcnt vmcnt(5)
	v_cvt_pk_bf16_f32 v104, v104, v105
	v_cvt_pk_bf16_f32 v105, v106, v107
	global_store_dwordx2 v102, v[104:105], s[26:27]
	s_waitcnt vmcnt(5)
	v_cvt_pk_bf16_f32 v108, v108, v109
	v_cvt_pk_bf16_f32 v109, v110, v111
	global_store_dwordx2 v102, v[108:109], s[28:29]
	s_waitcnt vmcnt(5)
	v_cvt_pk_bf16_f32 v112, v112, v113
	v_cvt_pk_bf16_f32 v113, v114, v115
	global_store_dwordx2 v102, v[112:113], s[30:31]
	s_waitcnt vmcnt(5)
	v_cvt_pk_bf16_f32 v116, v116, v117
	v_cvt_pk_bf16_f32 v117, v118, v119
	global_store_dwordx2 v103, v[116:117], s[30:31]
	s_waitcnt vmcnt(5)
	v_cvt_pk_bf16_f32 v120, v120, v121
	v_cvt_pk_bf16_f32 v121, v122, v123
	global_store_dwordx2 v102, v[120:121], s[88:89]
	s_waitcnt vmcnt(5)
	v_cvt_pk_bf16_f32 v124, v124, v125
	v_cvt_pk_bf16_f32 v125, v126, v127
	global_store_dwordx2 v103, v[124:125], s[88:89]
	s_branch .LBB0_99
	v_readlane_b32 s36, v247, 1
	v_or_b32_e32 v2, 8, v2
	v_readlane_b32 s40, v247, 5
	v_readlane_b32 s41, v247, 6
	s_ashr_i32 s1, s0, 31
	v_lshlrev_b64 v[4:5], 3, v[0:1]
	v_lshl_add_u64 v[6:7], s[40:41], 0, v[2:3]
	s_lshl_b64 s[6:7], s[0:1], 4
	v_lshl_add_u64 v[8:9], s[26:27], 0, v[4:5]
	s_lshl_b64 s[8:9], s[0:1], 3
	s_mov_b64 s[10:11], 0
	s_mov_b32 s1, 0x1ffff
	v_mov_b32_e32 v11, v0
	v_readlane_b32 s37, v247, 2
	v_readlane_b32 s38, v247, 3
	v_readlane_b32 s39, v247, 4
	v_readlane_b32 s42, v247, 7
	v_readlane_b32 s43, v247, 8
	v_readlane_b32 s44, v247, 9
	v_readlane_b32 s45, v247, 10
	v_readlane_b32 s46, v247, 11
	v_readlane_b32 s47, v247, 12
	v_readlane_b32 s48, v247, 13
	v_readlane_b32 s49, v247, 14
	v_readlane_b32 s50, v247, 15
	v_readlane_b32 s51, v247, 16
